# P9 SwiGLU epilogue and P7 mid-K hook: serialized row-scale loads issued together, one wait
# baseline (speedup 1.0000x reference)
.LBB0_543:
	s_cmpk_lg_i32 s38, 0x800
	s_cbranch_scc1 .LBB0_542
	global_load_dwordx2 v[202:203], v[132:133], off
	global_load_dwordx2 v[204:205], v[134:135], off
	global_load_dwordx2 v[206:207], v[136:137], off
	global_load_dwordx2 v[208:209], v[138:139], off
	global_load_dwordx2 v[210:211], v[140:141], off
	global_load_dwordx2 v[212:213], v[142:143], off
	global_load_dwordx2 v[214:215], v[144:145], off
	global_load_dwordx2 v[216:217], v[146:147], off
	s_waitcnt vmcnt(0)
	v_fmamk_f32 v1, v202, 0x3a800000, v191
	v_cmp_gt_f32_e32 vcc, s56, v1
	v_mul_f32_e32 v2, 0x4b800000, v1
	s_nop 0
	v_cndmask_b32_e32 v1, v1, v2, vcc
	v_rsq_f32_e32 v1, v1
	s_nop 0
	v_mul_f32_e32 v2, 0x45800000, v1
	v_cndmask_b32_e32 v1, v1, v2, vcc
	v_fmamk_f32 v2, v203, 0x3a800000, v191
	v_cmp_gt_f32_e32 vcc, s57, v2
	v_mul_f32_e32 v3, 0x4f800000, v2
	s_nop 0
	v_cndmask_b32_e32 v2, v2, v3, vcc
	v_sqrt_f32_e32 v3, v2
	s_nop 0
	v_add_u32_e32 v152, -1, v3
	v_fma_f32 v153, -v152, v3, v2
	v_cmp_ge_f32_e64 s[8:9], 0, v153
	v_add_u32_e32 v153, 1, v3
	s_nop 0
	v_cndmask_b32_e64 v152, v3, v152, s[8:9]
	v_fma_f32 v3, -v153, v3, v2
	v_cmp_lt_f32_e64 s[8:9], 0, v3
	s_nop 1
	v_cndmask_b32_e64 v3, v152, v153, s[8:9]
	v_mul_f32_e32 v152, 0x37800000, v3
	v_cndmask_b32_e32 v3, v3, v152, vcc
	v_cmp_class_f32_e32 vcc, v2, v192
	s_nop 1
	v_cndmask_b32_e32 v2, v3, v2, vcc
	v_mul_f32_e32 v2, v2, v1
	v_pk_mul_f32 v[130:131], v[130:131], v[2:3] op_sel_hi:[1,0]
	v_pk_mul_f32 v[128:129], v[128:129], v[2:3] op_sel_hi:[1,0]
	v_pk_mul_f32 v[126:127], v[126:127], v[2:3] op_sel_hi:[1,0]
	v_pk_mul_f32 v[124:125], v[124:125], v[2:3] op_sel_hi:[1,0]
	v_pk_mul_f32 v[122:123], v[122:123], v[2:3] op_sel_hi:[1,0]
	v_pk_mul_f32 v[120:121], v[120:121], v[2:3] op_sel_hi:[1,0]
	v_pk_mul_f32 v[118:119], v[118:119], v[2:3] op_sel_hi:[1,0]
	v_pk_mul_f32 v[116:117], v[116:117], v[2:3] op_sel_hi:[1,0]
	v_fmamk_f32 v1, v204, 0x3a800000, v191
	v_cmp_gt_f32_e32 vcc, s56, v1
	v_mul_f32_e32 v2, 0x4b800000, v1
	s_nop 0
	v_cndmask_b32_e32 v1, v1, v2, vcc
	v_rsq_f32_e32 v1, v1
	s_nop 0
	v_mul_f32_e32 v2, 0x45800000, v1
	v_cndmask_b32_e32 v1, v1, v2, vcc
	v_fmamk_f32 v2, v205, 0x3a800000, v191
	v_cmp_gt_f32_e32 vcc, s57, v2
	v_mul_f32_e32 v3, 0x4f800000, v2
	s_nop 0
	v_cndmask_b32_e32 v2, v2, v3, vcc
	v_sqrt_f32_e32 v3, v2
	s_nop 0
	v_add_u32_e32 v152, -1, v3
	v_fma_f32 v153, -v152, v3, v2
	v_cmp_ge_f32_e64 s[8:9], 0, v153
	v_add_u32_e32 v153, 1, v3
	s_nop 0
	v_cndmask_b32_e64 v152, v3, v152, s[8:9]
	v_fma_f32 v3, -v153, v3, v2
	v_cmp_lt_f32_e64 s[8:9], 0, v3
	s_nop 1
	v_cndmask_b32_e64 v3, v152, v153, s[8:9]
	v_mul_f32_e32 v152, 0x37800000, v3
	v_cndmask_b32_e32 v3, v3, v152, vcc
	v_cmp_class_f32_e32 vcc, v2, v192
	s_nop 1
	v_cndmask_b32_e32 v2, v3, v2, vcc
	v_mul_f32_e32 v2, v2, v1
	v_pk_mul_f32 v[114:115], v[114:115], v[2:3] op_sel_hi:[1,0]
	v_pk_mul_f32 v[112:113], v[112:113], v[2:3] op_sel_hi:[1,0]
	v_pk_mul_f32 v[110:111], v[110:111], v[2:3] op_sel_hi:[1,0]
	v_pk_mul_f32 v[108:109], v[108:109], v[2:3] op_sel_hi:[1,0]
	v_pk_mul_f32 v[106:107], v[106:107], v[2:3] op_sel_hi:[1,0]
	v_pk_mul_f32 v[104:105], v[104:105], v[2:3] op_sel_hi:[1,0]
	v_pk_mul_f32 v[102:103], v[102:103], v[2:3] op_sel_hi:[1,0]
	v_pk_mul_f32 v[100:101], v[100:101], v[2:3] op_sel_hi:[1,0]
	v_fmamk_f32 v1, v206, 0x3a800000, v191
	v_cmp_gt_f32_e32 vcc, s56, v1
	v_mul_f32_e32 v2, 0x4b800000, v1
	s_nop 0
	v_cndmask_b32_e32 v1, v1, v2, vcc
	v_rsq_f32_e32 v1, v1
	s_nop 0
	v_mul_f32_e32 v2, 0x45800000, v1
	v_cndmask_b32_e32 v1, v1, v2, vcc
	v_fmamk_f32 v2, v207, 0x3a800000, v191
	v_cmp_gt_f32_e32 vcc, s57, v2
	v_mul_f32_e32 v3, 0x4f800000, v2
	s_nop 0
	v_cndmask_b32_e32 v2, v2, v3, vcc
	v_sqrt_f32_e32 v3, v2
	s_nop 0
	v_add_u32_e32 v152, -1, v3
	v_fma_f32 v153, -v152, v3, v2
	v_cmp_ge_f32_e64 s[8:9], 0, v153
	v_add_u32_e32 v153, 1, v3
	s_nop 0
	v_cndmask_b32_e64 v152, v3, v152, s[8:9]
	v_fma_f32 v3, -v153, v3, v2
	v_cmp_lt_f32_e64 s[8:9], 0, v3
	s_nop 1
	v_cndmask_b32_e64 v3, v152, v153, s[8:9]
	v_mul_f32_e32 v152, 0x37800000, v3
	v_cndmask_b32_e32 v3, v3, v152, vcc
	v_cmp_class_f32_e32 vcc, v2, v192
	s_nop 1
	v_cndmask_b32_e32 v2, v3, v2, vcc
	v_mul_f32_e32 v2, v2, v1
	v_pk_mul_f32 v[98:99], v[98:99], v[2:3] op_sel_hi:[1,0]
	v_pk_mul_f32 v[96:97], v[96:97], v[2:3] op_sel_hi:[1,0]
	v_pk_mul_f32 v[94:95], v[94:95], v[2:3] op_sel_hi:[1,0]
	v_pk_mul_f32 v[92:93], v[92:93], v[2:3] op_sel_hi:[1,0]
	v_pk_mul_f32 v[90:91], v[90:91], v[2:3] op_sel_hi:[1,0]
	v_pk_mul_f32 v[88:89], v[88:89], v[2:3] op_sel_hi:[1,0]
	v_pk_mul_f32 v[86:87], v[86:87], v[2:3] op_sel_hi:[1,0]
	v_pk_mul_f32 v[84:85], v[84:85], v[2:3] op_sel_hi:[1,0]
	v_fmamk_f32 v1, v208, 0x3a800000, v191
	v_cmp_gt_f32_e32 vcc, s56, v1
	v_mul_f32_e32 v2, 0x4b800000, v1
	s_nop 0
	v_cndmask_b32_e32 v1, v1, v2, vcc
	v_rsq_f32_e32 v1, v1
	s_nop 0
	v_mul_f32_e32 v2, 0x45800000, v1
	v_cndmask_b32_e32 v1, v1, v2, vcc
	v_fmamk_f32 v2, v209, 0x3a800000, v191
	v_cmp_gt_f32_e32 vcc, s57, v2
	v_mul_f32_e32 v3, 0x4f800000, v2
	s_nop 0
	v_cndmask_b32_e32 v2, v2, v3, vcc
	v_sqrt_f32_e32 v3, v2
	s_nop 0
	v_add_u32_e32 v152, -1, v3
	v_fma_f32 v153, -v152, v3, v2
	v_cmp_ge_f32_e64 s[8:9], 0, v153
	v_add_u32_e32 v153, 1, v3
	s_nop 0
	v_cndmask_b32_e64 v152, v3, v152, s[8:9]
	v_fma_f32 v3, -v153, v3, v2
	v_cmp_lt_f32_e64 s[8:9], 0, v3
	s_nop 1
	v_cndmask_b32_e64 v3, v152, v153, s[8:9]
	v_mul_f32_e32 v152, 0x37800000, v3
	v_cndmask_b32_e32 v3, v3, v152, vcc
	v_cmp_class_f32_e32 vcc, v2, v192
	s_nop 1
	v_cndmask_b32_e32 v2, v3, v2, vcc
	v_mul_f32_e32 v2, v2, v1
	v_pk_mul_f32 v[82:83], v[82:83], v[2:3] op_sel_hi:[1,0]
	v_pk_mul_f32 v[80:81], v[80:81], v[2:3] op_sel_hi:[1,0]
	v_pk_mul_f32 v[78:79], v[78:79], v[2:3] op_sel_hi:[1,0]
	v_pk_mul_f32 v[76:77], v[76:77], v[2:3] op_sel_hi:[1,0]
	v_pk_mul_f32 v[74:75], v[74:75], v[2:3] op_sel_hi:[1,0]
	v_pk_mul_f32 v[72:73], v[72:73], v[2:3] op_sel_hi:[1,0]
	v_pk_mul_f32 v[70:71], v[70:71], v[2:3] op_sel_hi:[1,0]
	v_pk_mul_f32 v[68:69], v[68:69], v[2:3] op_sel_hi:[1,0]
	v_fmamk_f32 v1, v210, 0x3a800000, v191
	v_cmp_gt_f32_e32 vcc, s56, v1
	v_mul_f32_e32 v2, 0x4b800000, v1
	s_nop 0
	v_cndmask_b32_e32 v1, v1, v2, vcc
	v_rsq_f32_e32 v1, v1
	s_nop 0
	v_mul_f32_e32 v2, 0x45800000, v1
	v_cndmask_b32_e32 v1, v1, v2, vcc
	v_fmamk_f32 v2, v211, 0x3a800000, v191
	v_cmp_gt_f32_e32 vcc, s57, v2
	v_mul_f32_e32 v3, 0x4f800000, v2
	s_nop 0
	v_cndmask_b32_e32 v2, v2, v3, vcc
	v_sqrt_f32_e32 v3, v2
	s_nop 0
	v_add_u32_e32 v152, -1, v3
	v_fma_f32 v153, -v152, v3, v2
	v_cmp_ge_f32_e64 s[8:9], 0, v153
	v_add_u32_e32 v153, 1, v3
	s_nop 0
	v_cndmask_b32_e64 v152, v3, v152, s[8:9]
	v_fma_f32 v3, -v153, v3, v2
	v_cmp_lt_f32_e64 s[8:9], 0, v3
	s_nop 1
	v_cndmask_b32_e64 v3, v152, v153, s[8:9]
	v_mul_f32_e32 v152, 0x37800000, v3
	v_cndmask_b32_e32 v3, v3, v152, vcc
	v_cmp_class_f32_e32 vcc, v2, v192
	s_nop 1
	v_cndmask_b32_e32 v2, v3, v2, vcc
	v_mul_f32_e32 v2, v2, v1
	v_pk_mul_f32 v[66:67], v[66:67], v[2:3] op_sel_hi:[1,0]
	v_pk_mul_f32 v[64:65], v[64:65], v[2:3] op_sel_hi:[1,0]
	v_pk_mul_f32 v[62:63], v[62:63], v[2:3] op_sel_hi:[1,0]
	v_pk_mul_f32 v[60:61], v[60:61], v[2:3] op_sel_hi:[1,0]
	v_pk_mul_f32 v[58:59], v[58:59], v[2:3] op_sel_hi:[1,0]
	v_pk_mul_f32 v[56:57], v[56:57], v[2:3] op_sel_hi:[1,0]
	v_pk_mul_f32 v[54:55], v[54:55], v[2:3] op_sel_hi:[1,0]
	v_pk_mul_f32 v[52:53], v[52:53], v[2:3] op_sel_hi:[1,0]
	v_fmamk_f32 v1, v212, 0x3a800000, v191
	v_cmp_gt_f32_e32 vcc, s56, v1
	v_mul_f32_e32 v2, 0x4b800000, v1
	s_nop 0
	v_cndmask_b32_e32 v1, v1, v2, vcc
	v_rsq_f32_e32 v1, v1
	s_nop 0
	v_mul_f32_e32 v2, 0x45800000, v1
	v_cndmask_b32_e32 v1, v1, v2, vcc
	v_fmamk_f32 v2, v213, 0x3a800000, v191
	v_cmp_gt_f32_e32 vcc, s57, v2
	v_mul_f32_e32 v3, 0x4f800000, v2
	s_nop 0
	v_cndmask_b32_e32 v2, v2, v3, vcc
	v_sqrt_f32_e32 v3, v2
	s_nop 0
	v_add_u32_e32 v152, -1, v3
	v_fma_f32 v153, -v152, v3, v2
	v_cmp_ge_f32_e64 s[8:9], 0, v153
	v_add_u32_e32 v153, 1, v3
	s_nop 0
	v_cndmask_b32_e64 v152, v3, v152, s[8:9]
	v_fma_f32 v3, -v153, v3, v2
	v_cmp_lt_f32_e64 s[8:9], 0, v3
	s_nop 1
	v_cndmask_b32_e64 v3, v152, v153, s[8:9]
	v_mul_f32_e32 v152, 0x37800000, v3
	v_cndmask_b32_e32 v3, v3, v152, vcc
	v_cmp_class_f32_e32 vcc, v2, v192
	s_nop 1
	v_cndmask_b32_e32 v2, v3, v2, vcc
	v_mul_f32_e32 v2, v2, v1
	v_pk_mul_f32 v[50:51], v[50:51], v[2:3] op_sel_hi:[1,0]
	v_pk_mul_f32 v[48:49], v[48:49], v[2:3] op_sel_hi:[1,0]
	v_pk_mul_f32 v[46:47], v[46:47], v[2:3] op_sel_hi:[1,0]
	v_pk_mul_f32 v[44:45], v[44:45], v[2:3] op_sel_hi:[1,0]
	v_pk_mul_f32 v[42:43], v[42:43], v[2:3] op_sel_hi:[1,0]
	v_pk_mul_f32 v[40:41], v[40:41], v[2:3] op_sel_hi:[1,0]
	v_pk_mul_f32 v[38:39], v[38:39], v[2:3] op_sel_hi:[1,0]
	v_pk_mul_f32 v[36:37], v[36:37], v[2:3] op_sel_hi:[1,0]
	v_fmamk_f32 v1, v214, 0x3a800000, v191
	v_cmp_gt_f32_e32 vcc, s56, v1
	v_mul_f32_e32 v2, 0x4b800000, v1
	s_nop 0
	v_cndmask_b32_e32 v1, v1, v2, vcc
	v_rsq_f32_e32 v1, v1
	s_nop 0
	v_mul_f32_e32 v2, 0x45800000, v1
	v_cndmask_b32_e32 v1, v1, v2, vcc
	v_fmamk_f32 v2, v215, 0x3a800000, v191
	v_cmp_gt_f32_e32 vcc, s57, v2
	v_mul_f32_e32 v3, 0x4f800000, v2
	s_nop 0
	v_cndmask_b32_e32 v2, v2, v3, vcc
	v_sqrt_f32_e32 v3, v2
	s_nop 0
	v_add_u32_e32 v152, -1, v3
	v_fma_f32 v153, -v152, v3, v2
	v_cmp_ge_f32_e64 s[8:9], 0, v153
	v_add_u32_e32 v153, 1, v3
	s_nop 0
	v_cndmask_b32_e64 v152, v3, v152, s[8:9]
	v_fma_f32 v3, -v153, v3, v2
	v_cmp_lt_f32_e64 s[8:9], 0, v3
	s_nop 1
	v_cndmask_b32_e64 v3, v152, v153, s[8:9]
	v_mul_f32_e32 v152, 0x37800000, v3
	v_cndmask_b32_e32 v3, v3, v152, vcc
	v_cmp_class_f32_e32 vcc, v2, v192
	s_nop 1
	v_cndmask_b32_e32 v2, v3, v2, vcc
	v_mul_f32_e32 v2, v2, v1
	v_pk_mul_f32 v[34:35], v[34:35], v[2:3] op_sel_hi:[1,0]
	v_pk_mul_f32 v[32:33], v[32:33], v[2:3] op_sel_hi:[1,0]
	v_pk_mul_f32 v[30:31], v[30:31], v[2:3] op_sel_hi:[1,0]
	v_pk_mul_f32 v[28:29], v[28:29], v[2:3] op_sel_hi:[1,0]
	v_pk_mul_f32 v[26:27], v[26:27], v[2:3] op_sel_hi:[1,0]
	v_pk_mul_f32 v[24:25], v[24:25], v[2:3] op_sel_hi:[1,0]
	v_pk_mul_f32 v[22:23], v[22:23], v[2:3] op_sel_hi:[1,0]
	v_pk_mul_f32 v[20:21], v[20:21], v[2:3] op_sel_hi:[1,0]
	v_fmamk_f32 v1, v216, 0x3a800000, v191
	v_cmp_gt_f32_e32 vcc, s56, v1
	v_mul_f32_e32 v2, 0x4b800000, v1
	s_nop 0
	v_cndmask_b32_e32 v1, v1, v2, vcc
	v_rsq_f32_e32 v1, v1
	s_nop 0
	v_mul_f32_e32 v2, 0x45800000, v1
	v_cndmask_b32_e32 v1, v1, v2, vcc
	v_fmamk_f32 v2, v217, 0x3a800000, v191
	v_cmp_gt_f32_e32 vcc, s57, v2
	v_mul_f32_e32 v3, 0x4f800000, v2
	s_nop 0
	v_cndmask_b32_e32 v2, v2, v3, vcc
	v_sqrt_f32_e32 v3, v2
	s_nop 0
	v_add_u32_e32 v152, -1, v3
	v_fma_f32 v153, -v152, v3, v2
	v_cmp_ge_f32_e64 s[8:9], 0, v153
	v_add_u32_e32 v153, 1, v3
	s_nop 0
	v_cndmask_b32_e64 v152, v3, v152, s[8:9]
	v_fma_f32 v3, -v153, v3, v2
	v_cmp_lt_f32_e64 s[8:9], 0, v3
	s_nop 1
	v_cndmask_b32_e64 v3, v152, v153, s[8:9]
	v_mul_f32_e32 v152, 0x37800000, v3
	v_cndmask_b32_e32 v3, v3, v152, vcc
	v_cmp_class_f32_e32 vcc, v2, v192
	s_nop 1
	v_cndmask_b32_e32 v2, v3, v2, vcc
	v_mul_f32_e32 v2, v2, v1
	v_pk_mul_f32 v[18:19], v[18:19], v[2:3] op_sel_hi:[1,0]
	v_pk_mul_f32 v[16:17], v[16:17], v[2:3] op_sel_hi:[1,0]
	v_pk_mul_f32 v[14:15], v[14:15], v[2:3] op_sel_hi:[1,0]
	v_pk_mul_f32 v[12:13], v[12:13], v[2:3] op_sel_hi:[1,0]
	v_pk_mul_f32 v[10:11], v[10:11], v[2:3] op_sel_hi:[1,0]
	v_pk_mul_f32 v[8:9], v[8:9], v[2:3] op_sel_hi:[1,0]
	v_pk_mul_f32 v[6:7], v[6:7], v[2:3] op_sel_hi:[1,0]
	v_pk_mul_f32 v[4:5], v[4:5], v[2:3] op_sel_hi:[1,0]
	s_branch .LBB0_542
